# GEMM K-loops: dropped the redundant post-barrier lgkmcnt(0) and the mid-block setprio 0/1 toggles
# speedup vs baseline: 1.0034x; 1.0034x over previous
; #define PG8_STAGE(bufoff, gbase, voff) do { _Pragma("unroll") for (int _i = 0; _i < 2; ++_i) \
;         __builtin_amdgcn_global_load_lds((const unsigned*)((const char*)(gbase) + (voff)[_i]), (PG8_LAS unsigned*)(lds + (bufoff) + ldsw + _i * 8192), 16, 0, 0); } while (0)
; #define PG8_LDA(dst, b, h) do { _Pragma("unroll") for (int m = 0; m < 4; ++m) _Pragma("unroll") for (int k = 0; k < 2; ++k) dst[m][k] = *(const PG8_LAS bf16x8*)(lds + PG8_SA(b, h) + aoff + m * 2048 + k * 1024); } while (0)
; #define PG8_LDB(dst, b, h) do { _Pragma("unroll") for (int n = 0; n < 2; ++n) _Pragma("unroll") for (int k = 0; k < 2; ++k) dst[n][k] = *(const PG8_LAS bf16x8*)(lds + PG8_SB(b, h) + boff + n * 2048 + k * 1024); } while (0)
; #define PG8_MMA(ai, bj, At, Bt) do { __builtin_amdgcn_s_setprio(1); _Pragma("unroll") for (int m = 0; m < 4; ++m) _Pragma("unroll") for (int n = 0; n < 2; ++n) _Pragma("unroll") for (int k = 0; k < 2; ++k) \
;         acc[ai][bj][m][n] = __builtin_amdgcn_mfma_f32_16x16x32_bf16(Bt[n][k], At[m][k], acc[ai][bj][m][n], 0, 0, 0); __builtin_amdgcn_s_setprio(0); } while (0)
; #define PG8_WAIT_V(n) asm volatile("s_waitcnt vmcnt(" #n ")" ::: "memory")
; #define PG8_WAIT_L(n) asm volatile("s_waitcnt lgkmcnt(" #n ")" ::: "memory")
; #define PG8_BAR __builtin_amdgcn_s_barrier()
; #define PG8_SCHED __builtin_amdgcn_sched_barrier(0)
; template <class Epi, class Sched, bool ALIGN_EPI = false, bool SP2 = false, class Hook = NoHook>
; __device__ __forceinline__ void gemm_phase(PG8_LAS unsigned char* lds, const Gemm g, const Sched& S, const Epi& E, int tid, const Hook& H = Hook()) {
;     ...
;             PG8_LDB(B0, 0, 0); PG8_LDB(B1, 0, 1); PG8_SCHED; PG8_LDA(At, 0, 0); PG8_STAGE(PG8_SA(1, 1), a1 + hstep, voffA);
;             PG8_WAIT_V(8); PG8_WAIT_L(0); PG8_BAR; PG8_MMA(0, 0, At, B0); PG8_MMA(0, 1, At, B1); PG8_BAR; PG8_SCHED;
;             PG8_LDA(At, 0, 1); PG8_STAGE(PG8_SB(0, 0), b2, voffB); PG8_STAGE(PG8_SB(0, 1), b2 + hstep, voffB); PG8_STAGE(PG8_SA(0, 0), a2, voffA);
.LBB0_126:
	s_add_u32 s39, s46, s54
	s_addc_u32 s48, s47, s55
	s_add_u32 s39, s39, 0x100
	s_addc_u32 s48, s48, 0
	s_add_u32 s62, s94, s54
	s_addc_u32 s49, s95, s55
	s_add_i32 s63, 0, 0x10000
	s_cmpk_eq_i32 s54, 0xb00
	s_cselect_b32 s59, s1, s48
	s_cselect_b32 s58, s0, s39
	v_add_u32_e32 v96, s63, v156
	s_cselect_b32 s49, s45, s49
	s_cselect_b32 s48, s44, s62
	s_add_i32 s39, 0, 0x14000
	ds_read_b128 v[138:141], v96
	ds_read_b128 v[148:151], v96 offset:1024
	ds_read_b128 v[158:161], v96 offset:2048
	ds_read_b128 v[162:165], v96 offset:3072
	v_add_u32_e32 v96, s39, v156
	ds_read_b128 v[166:169], v96
	ds_read_b128 v[170:173], v96 offset:1024
	ds_read_b128 v[174:177], v96 offset:2048
	ds_read_b128 v[178:181], v96 offset:3072
	v_lshl_add_u64 v[98:99], v[144:145], 0, s[54:55]
	s_add_i32 m0, s61, 0xc000
	ds_read_b128 v[182:185], v157
	ds_read_b128 v[186:189], v157 offset:1024
	ds_read_b128 v[190:193], v157 offset:2048
	ds_read_b128 v[194:197], v157 offset:3072
	ds_read_b128 v[198:201], v157 offset:4096
	ds_read_b128 v[202:205], v157 offset:5120
	ds_read_b128 v[206:209], v157 offset:6144
	ds_read_b128 v[230:233], v157 offset:7168
	global_load_lds_dwordx4 v[98:99], off
	v_lshl_add_u64 v[98:99], v[146:147], 0, s[54:55]
	s_add_i32 m0, s61, 0xe000
	s_nop 0
	global_load_lds_dwordx4 v[98:99], off
	s_waitcnt vmcnt(8)
	s_waitcnt lgkmcnt(0)
	s_barrier
	s_setprio 1
	v_mfma_f32_16x16x32_bf16 v[128:131], v[138:141], v[182:185], v[128:131]
	v_mfma_f32_16x16x32_bf16 v[124:127], v[158:161], v[182:185], v[124:127]
	v_mfma_f32_16x16x32_bf16 v[112:115], v[138:141], v[190:193], v[112:115]
	v_mfma_f32_16x16x32_bf16 v[108:111], v[158:161], v[190:193], v[108:111]
	v_mfma_f32_16x16x32_bf16 v[92:95], v[138:141], v[198:201], v[92:95]
	v_mfma_f32_16x16x32_bf16 v[88:91], v[158:161], v[198:201], v[88:91]
	v_mfma_f32_16x16x32_bf16 v[76:79], v[138:141], v[206:209], v[76:79]
	v_mfma_f32_16x16x32_bf16 v[72:75], v[158:161], v[206:209], v[72:75]
	v_mfma_f32_16x16x32_bf16 v[128:131], v[148:151], v[186:189], v[128:131]
	v_mfma_f32_16x16x32_bf16 v[124:127], v[162:165], v[186:189], v[124:127]
	v_mfma_f32_16x16x32_bf16 v[112:115], v[148:151], v[194:197], v[112:115]
	v_mfma_f32_16x16x32_bf16 v[108:111], v[162:165], v[194:197], v[108:111]
	v_mfma_f32_16x16x32_bf16 v[92:95], v[148:151], v[202:205], v[92:95]
	v_mfma_f32_16x16x32_bf16 v[88:91], v[162:165], v[202:205], v[88:91]
	v_mfma_f32_16x16x32_bf16 v[76:79], v[148:151], v[230:233], v[76:79]
	v_mfma_f32_16x16x32_bf16 v[72:75], v[162:165], v[230:233], v[72:75]
	v_mfma_f32_16x16x32_bf16 v[120:123], v[166:169], v[182:185], v[120:123]
	v_mfma_f32_16x16x32_bf16 v[116:119], v[174:177], v[182:185], v[116:119]
	v_mfma_f32_16x16x32_bf16 v[104:107], v[166:169], v[190:193], v[104:107]
	v_mfma_f32_16x16x32_bf16 v[98:101], v[174:177], v[190:193], v[100:103]
	v_mfma_f32_16x16x32_bf16 v[84:87], v[166:169], v[198:201], v[84:87]
	v_mfma_f32_16x16x32_bf16 v[80:83], v[174:177], v[198:201], v[80:83]
	v_mfma_f32_16x16x32_bf16 v[68:71], v[166:169], v[206:209], v[68:71]
	v_mfma_f32_16x16x32_bf16 v[64:67], v[174:177], v[206:209], v[64:67]
	v_mfma_f32_16x16x32_bf16 v[120:123], v[170:173], v[186:189], v[120:123]
	v_mfma_f32_16x16x32_bf16 v[116:119], v[178:181], v[186:189], v[116:119]
	v_mfma_f32_16x16x32_bf16 v[104:107], v[170:173], v[194:197], v[104:107]
	v_mfma_f32_16x16x32_bf16 v[98:101], v[178:181], v[194:197], v[98:101]
	v_mfma_f32_16x16x32_bf16 v[84:87], v[170:173], v[202:205], v[84:87]
	v_mfma_f32_16x16x32_bf16 v[80:83], v[178:181], v[202:205], v[80:83]
	v_mfma_f32_16x16x32_bf16 v[68:71], v[170:173], v[230:233], v[68:71]
	v_mfma_f32_16x16x32_bf16 v[64:67], v[178:181], v[230:233], v[64:67]
	s_setprio 0
	s_barrier
	s_add_i32 s62, s63, s27
	v_lshl_add_u64 v[152:153], s[48:49], 0, v[134:135]
	s_mov_b32 m0, s62
	ds_read_b128 v[182:185], v157 offset:16384
	ds_read_b128 v[186:189], v157 offset:17408
	ds_read_b128 v[190:193], v157 offset:18432
	ds_read_b128 v[194:197], v157 offset:19456
	ds_read_b128 v[198:201], v157 offset:20480
	ds_read_b128 v[202:205], v157 offset:21504
	ds_read_b128 v[206:209], v157 offset:22528
	ds_read_b128 v[230:233], v157 offset:23552
	global_load_lds_dwordx4 v[152:153], off
	s_add_i32 m0, s62, 0x2000
	s_add_u32 s62, s48, 0x60000
	v_lshl_add_u64 v[234:235], s[48:49], 0, v[132:133]
	s_addc_u32 s63, s49, 0
	s_add_i32 s39, s39, s27
	global_load_lds_dwordx4 v[234:235], off
	v_lshl_add_u64 v[102:103], s[62:63], 0, v[134:135]
	s_mov_b32 m0, s39
	v_lshl_add_u64 v[236:237], s[58:59], 0, v[134:135]
	global_load_lds_dwordx4 v[102:103], off
	v_lshl_add_u64 v[102:103], s[62:63], 0, v[132:133]
	s_add_i32 m0, s39, 0x2000
	v_lshl_add_u64 v[238:239], s[58:59], 0, v[132:133]
	global_load_lds_dwordx4 v[102:103], off
	s_mov_b32 m0, s61
	s_nop 0
	global_load_lds_dwordx4 v[236:237], off
	s_mov_b32 m0, s64
	s_nop 0
	global_load_lds_dwordx4 v[238:239], off
	s_waitcnt vmcnt(8)
	s_waitcnt lgkmcnt(0)
	s_barrier
; #define PG8_STAGE(bufoff, gbase, voff) do { _Pragma("unroll") for (int _i = 0; _i < 2; ++_i) \
;         __builtin_amdgcn_global_load_lds((const unsigned*)((const char*)(gbase) + (voff)[_i]), (PG8_LAS unsigned*)(lds + (bufoff) + ldsw + _i * 8192), 16, 0, 0); } while (0)
; #define PG8_LDA(dst, b, h) do { _Pragma("unroll") for (int m = 0; m < 4; ++m) _Pragma("unroll") for (int k = 0; k < 2; ++k) dst[m][k] = *(const PG8_LAS bf16x8*)(lds + PG8_SA(b, h) + aoff + m * 2048 + k * 1024); } while (0)
; #define PG8_LDB(dst, b, h) do { _Pragma("unroll") for (int n = 0; n < 2; ++n) _Pragma("unroll") for (int k = 0; k < 2; ++k) dst[n][k] = *(const PG8_LAS bf16x8*)(lds + PG8_SB(b, h) + boff + n * 2048 + k * 1024); } while (0)
; #define PG8_MMA(ai, bj, At, Bt) do { __builtin_amdgcn_s_setprio(1); _Pragma("unroll") for (int m = 0; m < 4; ++m) _Pragma("unroll") for (int n = 0; n < 2; ++n) _Pragma("unroll") for (int k = 0; k < 2; ++k) \
;         acc[ai][bj][m][n] = __builtin_amdgcn_mfma_f32_16x16x32_bf16(Bt[n][k], At[m][k], acc[ai][bj][m][n], 0, 0, 0); __builtin_amdgcn_s_setprio(0); } while (0)
; #define PG8_WAIT_V(n) asm volatile("s_waitcnt vmcnt(" #n ")" ::: "memory")
; #define PG8_WAIT_L(n) asm volatile("s_waitcnt lgkmcnt(" #n ")" ::: "memory")
; #define PG8_BAR __builtin_amdgcn_s_barrier()
; #define PG8_SCHED __builtin_amdgcn_sched_barrier(0)
; template <class Epi, class Sched, bool ALIGN_EPI = false, bool SP2 = false, class Hook = NoHook>
; __device__ __forceinline__ void gemm_phase(PG8_LAS unsigned char* lds, const Gemm g, const Sched& S, const Epi& E, int tid, const Hook& H = Hook()) {
;     ...
;             PG8_WAIT_V(8); PG8_WAIT_L(0); PG8_BAR; PG8_MMA(1, 0, At, B0); PG8_MMA(1, 1, At, B1); PG8_BAR; PG8_SCHED;
;             PG8_LDB(B0, 1, 0); PG8_LDB(B1, 1, 1); PG8_SCHED; PG8_LDA(At, 1, 0); PG8_STAGE(PG8_SA(0, 1), a2 + hstep, voffA);
;             PG8_WAIT_V(8); PG8_WAIT_L(0); PG8_BAR; PG8_MMA(0, 0, At, B0); PG8_MMA(0, 1, At, B1); PG8_BAR; PG8_SCHED;
	s_setprio 1
	v_mfma_f32_16x16x32_bf16 v[60:63], v[138:141], v[182:185], v[60:63]
	v_mfma_f32_16x16x32_bf16 v[56:59], v[158:161], v[182:185], v[56:59]
	v_mfma_f32_16x16x32_bf16 v[44:47], v[138:141], v[190:193], v[44:47]
	v_mfma_f32_16x16x32_bf16 v[40:43], v[158:161], v[190:193], v[40:43]
	v_mfma_f32_16x16x32_bf16 v[28:31], v[138:141], v[198:201], v[28:31]
	v_mfma_f32_16x16x32_bf16 v[24:27], v[158:161], v[198:201], v[24:27]
	v_mfma_f32_16x16x32_bf16 v[12:15], v[138:141], v[206:209], v[12:15]
	v_mfma_f32_16x16x32_bf16 v[8:11], v[158:161], v[206:209], v[8:11]
	v_mfma_f32_16x16x32_bf16 v[60:63], v[148:151], v[186:189], v[60:63]
	v_mfma_f32_16x16x32_bf16 v[56:59], v[162:165], v[186:189], v[56:59]
	v_mfma_f32_16x16x32_bf16 v[44:47], v[148:151], v[194:197], v[44:47]
	v_mfma_f32_16x16x32_bf16 v[40:43], v[162:165], v[194:197], v[40:43]
	v_mfma_f32_16x16x32_bf16 v[28:31], v[148:151], v[202:205], v[28:31]
	v_mfma_f32_16x16x32_bf16 v[24:27], v[162:165], v[202:205], v[24:27]
	v_mfma_f32_16x16x32_bf16 v[12:15], v[148:151], v[230:233], v[12:15]
	v_mfma_f32_16x16x32_bf16 v[8:11], v[162:165], v[230:233], v[8:11]
	v_mfma_f32_16x16x32_bf16 v[52:55], v[166:169], v[182:185], v[52:55]
	v_mfma_f32_16x16x32_bf16 v[48:51], v[174:177], v[182:185], v[48:51]
	v_mfma_f32_16x16x32_bf16 v[36:39], v[166:169], v[190:193], v[36:39]
	v_mfma_f32_16x16x32_bf16 v[32:35], v[174:177], v[190:193], v[32:35]
	v_mfma_f32_16x16x32_bf16 v[20:23], v[166:169], v[198:201], v[20:23]
	v_mfma_f32_16x16x32_bf16 v[16:19], v[174:177], v[198:201], v[16:19]
	v_mfma_f32_16x16x32_bf16 v[4:7], v[166:169], v[206:209], v[4:7]
	v_mfma_f32_16x16x32_bf16 v[0:3], v[174:177], v[206:209], v[0:3]
	v_mfma_f32_16x16x32_bf16 v[52:55], v[170:173], v[186:189], v[52:55]
	v_mfma_f32_16x16x32_bf16 v[48:51], v[178:181], v[186:189], v[48:51]
	v_mfma_f32_16x16x32_bf16 v[36:39], v[170:173], v[194:197], v[36:39]
	v_mfma_f32_16x16x32_bf16 v[32:35], v[178:181], v[194:197], v[32:35]
	v_mfma_f32_16x16x32_bf16 v[20:23], v[170:173], v[202:205], v[20:23]
	v_mfma_f32_16x16x32_bf16 v[16:19], v[178:181], v[202:205], v[16:19]
	v_mfma_f32_16x16x32_bf16 v[4:7], v[170:173], v[230:233], v[4:7]
	v_mfma_f32_16x16x32_bf16 v[0:3], v[178:181], v[230:233], v[0:3]
	s_setprio 0
	s_barrier
	s_add_i32 s39, 0, 0x18000
	v_add_u32_e32 v96, s39, v156
	s_add_i32 s62, 0, 0x1c000
	ds_read_b128 v[138:141], v96
	ds_read_b128 v[148:151], v96 offset:1024
	ds_read_b128 v[158:161], v96 offset:2048
	ds_read_b128 v[162:165], v96 offset:3072
	v_add_u32_e32 v96, s62, v156
	ds_read_b128 v[166:169], v96
	ds_read_b128 v[170:173], v96 offset:1024
	ds_read_b128 v[174:177], v96 offset:2048
	ds_read_b128 v[178:181], v96 offset:3072
	s_add_u32 s58, s58, 0x60000
	s_addc_u32 s59, s59, 0
	s_mov_b32 m0, s65
	v_lshl_add_u64 v[102:103], s[58:59], 0, v[134:135]
	ds_read_b128 v[182:185], v157 offset:32768
	ds_read_b128 v[186:189], v157 offset:33792
	ds_read_b128 v[190:193], v157 offset:34816
	ds_read_b128 v[194:197], v157 offset:35840
	ds_read_b128 v[198:201], v157 offset:36864
	ds_read_b128 v[202:205], v157 offset:37888
	ds_read_b128 v[206:209], v157 offset:38912
	ds_read_b128 v[230:233], v157 offset:39936
	global_load_lds_dwordx4 v[102:103], off
	v_lshl_add_u64 v[102:103], s[58:59], 0, v[132:133]
	s_mov_b32 m0, s72
	s_nop 0
	global_load_lds_dwordx4 v[102:103], off
	s_waitcnt vmcnt(8)
	s_waitcnt lgkmcnt(0)
	s_barrier
	s_setprio 1
	v_mfma_f32_16x16x32_bf16 v[128:131], v[138:141], v[182:185], v[128:131]
	v_mfma_f32_16x16x32_bf16 v[124:127], v[158:161], v[182:185], v[124:127]
	v_mfma_f32_16x16x32_bf16 v[112:115], v[138:141], v[190:193], v[112:115]
	v_mfma_f32_16x16x32_bf16 v[108:111], v[158:161], v[190:193], v[108:111]
	v_mfma_f32_16x16x32_bf16 v[92:95], v[138:141], v[198:201], v[92:95]
	v_mfma_f32_16x16x32_bf16 v[88:91], v[158:161], v[198:201], v[88:91]
	v_mfma_f32_16x16x32_bf16 v[76:79], v[138:141], v[206:209], v[76:79]
	v_mfma_f32_16x16x32_bf16 v[72:75], v[158:161], v[206:209], v[72:75]
	v_mfma_f32_16x16x32_bf16 v[128:131], v[148:151], v[186:189], v[128:131]
	v_mfma_f32_16x16x32_bf16 v[124:127], v[162:165], v[186:189], v[124:127]
	v_mfma_f32_16x16x32_bf16 v[112:115], v[148:151], v[194:197], v[112:115]
	v_mfma_f32_16x16x32_bf16 v[108:111], v[162:165], v[194:197], v[108:111]
	v_mfma_f32_16x16x32_bf16 v[92:95], v[148:151], v[202:205], v[92:95]
	v_mfma_f32_16x16x32_bf16 v[88:91], v[162:165], v[202:205], v[88:91]
	v_mfma_f32_16x16x32_bf16 v[76:79], v[148:151], v[230:233], v[76:79]
	v_mfma_f32_16x16x32_bf16 v[72:75], v[162:165], v[230:233], v[72:75]
	v_mfma_f32_16x16x32_bf16 v[120:123], v[166:169], v[182:185], v[120:123]
	v_mfma_f32_16x16x32_bf16 v[116:119], v[174:177], v[182:185], v[116:119]
	v_mfma_f32_16x16x32_bf16 v[102:105], v[166:169], v[190:193], v[104:107]
	v_mfma_f32_16x16x32_bf16 v[98:101], v[174:177], v[190:193], v[98:101]
	v_mfma_f32_16x16x32_bf16 v[84:87], v[166:169], v[198:201], v[84:87]
	v_mfma_f32_16x16x32_bf16 v[80:83], v[174:177], v[198:201], v[80:83]
	v_mfma_f32_16x16x32_bf16 v[68:71], v[166:169], v[206:209], v[68:71]
	v_mfma_f32_16x16x32_bf16 v[64:67], v[174:177], v[206:209], v[64:67]
	v_mfma_f32_16x16x32_bf16 v[120:123], v[170:173], v[186:189], v[120:123]
	v_mfma_f32_16x16x32_bf16 v[116:119], v[178:181], v[186:189], v[116:119]
	v_mfma_f32_16x16x32_bf16 v[104:107], v[170:173], v[194:197], v[102:105]
	v_mfma_f32_16x16x32_bf16 v[100:103], v[178:181], v[194:197], v[98:101]
	v_mfma_f32_16x16x32_bf16 v[84:87], v[170:173], v[202:205], v[84:87]
	v_mfma_f32_16x16x32_bf16 v[80:83], v[178:181], v[202:205], v[80:83]
	v_mfma_f32_16x16x32_bf16 v[68:71], v[170:173], v[230:233], v[68:71]
	v_mfma_f32_16x16x32_bf16 v[64:67], v[178:181], v[230:233], v[64:67]
	s_setprio 0
	s_barrier
; #define PG8_STAGE(bufoff, gbase, voff) do { _Pragma("unroll") for (int _i = 0; _i < 2; ++_i) \
;         __builtin_amdgcn_global_load_lds((const unsigned*)((const char*)(gbase) + (voff)[_i]), (PG8_LAS unsigned*)(lds + (bufoff) + ldsw + _i * 8192), 16, 0, 0); } while (0)
; #define PG8_LDA(dst, b, h) do { _Pragma("unroll") for (int m = 0; m < 4; ++m) _Pragma("unroll") for (int k = 0; k < 2; ++k) dst[m][k] = *(const PG8_LAS bf16x8*)(lds + PG8_SA(b, h) + aoff + m * 2048 + k * 1024); } while (0)
; #define PG8_MMA(ai, bj, At, Bt) do { __builtin_amdgcn_s_setprio(1); _Pragma("unroll") for (int m = 0; m < 4; ++m) _Pragma("unroll") for (int n = 0; n < 2; ++n) _Pragma("unroll") for (int k = 0; k < 2; ++k) \
;         acc[ai][bj][m][n] = __builtin_amdgcn_mfma_f32_16x16x32_bf16(Bt[n][k], At[m][k], acc[ai][bj][m][n], 0, 0, 0); __builtin_amdgcn_s_setprio(0); } while (0)
; #define PG8_WAIT_V(n) asm volatile("s_waitcnt vmcnt(" #n ")" ::: "memory")
; #define PG8_WAIT_L(n) asm volatile("s_waitcnt lgkmcnt(" #n ")" ::: "memory")
; #define PG8_BAR __builtin_amdgcn_s_barrier()
; #define PG8_SCHED __builtin_amdgcn_sched_barrier(0)
; template <class Epi, class Sched, bool ALIGN_EPI = false, bool SP2 = false, class Hook = NoHook>
; __device__ __forceinline__ void gemm_phase(PG8_LAS unsigned char* lds, const Gemm g, const Sched& S, const Epi& E, int tid, const Hook& H = Hook()) {
;     ...
;         for (int t = 0; t < nt; t += 2) {
;             if constexpr (Hook::ON) { if (t == 8 || t == 16) H(acc, cur, wr, wc, fr, fq, t); }
;     ...
;             PG8_LDA(At, 1, 1); PG8_STAGE(PG8_SB(1, 0), b3, voffB); PG8_STAGE(PG8_SB(1, 1), b3 + hstep, voffB); PG8_STAGE(PG8_SA(1, 0), a3, voffA);
;             PG8_WAIT_V(8); PG8_WAIT_L(0); PG8_BAR; PG8_MMA(1, 0, At, B0); PG8_MMA(1, 1, At, B1); PG8_BAR; PG8_SCHED;
	s_mov_b64 s[4:5], 0x80
	s_add_i32 s39, s39, s27
	v_lshl_add_u64 v[98:99], v[152:153], 0, s[4:5]
	s_mov_b32 m0, s39
	ds_read_b128 v[182:185], v157 offset:49152
	ds_read_b128 v[186:189], v157 offset:50176
	ds_read_b128 v[190:193], v157 offset:51200
	ds_read_b128 v[194:197], v157 offset:52224
	ds_read_b128 v[198:201], v157 offset:53248
	ds_read_b128 v[202:205], v157 offset:54272
	ds_read_b128 v[206:209], v157 offset:55296
	ds_read_b128 v[230:233], v157 offset:56320
	global_load_lds_dwordx4 v[98:99], off
	s_add_i32 m0, s39, 0x2000
	s_add_u32 s48, s48, 0x60080
	v_lshl_add_u64 v[98:99], v[234:235], 0, s[4:5]
	s_addc_u32 s49, s49, 0
	s_add_i32 s39, s62, s27
	global_load_lds_dwordx4 v[98:99], off
	v_lshl_add_u64 v[98:99], s[48:49], 0, v[134:135]
	s_mov_b32 m0, s39
	s_nop 0
	global_load_lds_dwordx4 v[98:99], off
	v_lshl_add_u64 v[98:99], s[48:49], 0, v[132:133]
	s_add_i32 m0, s39, 0x2000
	s_nop 0
	global_load_lds_dwordx4 v[98:99], off
	v_lshl_add_u64 v[98:99], v[236:237], 0, s[4:5]
	s_mov_b32 m0, s75
	s_nop 0
	global_load_lds_dwordx4 v[98:99], off
	v_lshl_add_u64 v[98:99], v[238:239], 0, s[4:5]
	s_mov_b32 m0, s76
	s_nop 0
	global_load_lds_dwordx4 v[98:99], off
	s_waitcnt vmcnt(8)
	s_waitcnt lgkmcnt(0)
	s_barrier
	s_setprio 1
	v_mfma_f32_16x16x32_bf16 v[60:63], v[138:141], v[182:185], v[60:63]
	v_mfma_f32_16x16x32_bf16 v[56:59], v[158:161], v[182:185], v[56:59]
	v_mfma_f32_16x16x32_bf16 v[44:47], v[138:141], v[190:193], v[44:47]
	v_mfma_f32_16x16x32_bf16 v[40:43], v[158:161], v[190:193], v[40:43]
	v_mfma_f32_16x16x32_bf16 v[28:31], v[138:141], v[198:201], v[28:31]
	v_mfma_f32_16x16x32_bf16 v[24:27], v[158:161], v[198:201], v[24:27]
	v_mfma_f32_16x16x32_bf16 v[12:15], v[138:141], v[206:209], v[12:15]
	v_mfma_f32_16x16x32_bf16 v[8:11], v[158:161], v[206:209], v[8:11]
	v_mfma_f32_16x16x32_bf16 v[60:63], v[148:151], v[186:189], v[60:63]
	v_mfma_f32_16x16x32_bf16 v[56:59], v[162:165], v[186:189], v[56:59]
	v_mfma_f32_16x16x32_bf16 v[44:47], v[148:151], v[194:197], v[44:47]
	v_mfma_f32_16x16x32_bf16 v[40:43], v[162:165], v[194:197], v[40:43]
	v_mfma_f32_16x16x32_bf16 v[28:31], v[148:151], v[202:205], v[28:31]
	v_mfma_f32_16x16x32_bf16 v[24:27], v[162:165], v[202:205], v[24:27]
	v_mfma_f32_16x16x32_bf16 v[12:15], v[148:151], v[230:233], v[12:15]
	v_mfma_f32_16x16x32_bf16 v[8:11], v[162:165], v[230:233], v[8:11]
	v_mfma_f32_16x16x32_bf16 v[52:55], v[166:169], v[182:185], v[52:55]
	v_mfma_f32_16x16x32_bf16 v[48:51], v[174:177], v[182:185], v[48:51]
	v_mfma_f32_16x16x32_bf16 v[36:39], v[166:169], v[190:193], v[36:39]
	v_mfma_f32_16x16x32_bf16 v[32:35], v[174:177], v[190:193], v[32:35]
	v_mfma_f32_16x16x32_bf16 v[20:23], v[166:169], v[198:201], v[20:23]
	v_mfma_f32_16x16x32_bf16 v[16:19], v[174:177], v[198:201], v[16:19]
	v_mfma_f32_16x16x32_bf16 v[4:7], v[166:169], v[206:209], v[4:7]
	v_mfma_f32_16x16x32_bf16 v[0:3], v[174:177], v[206:209], v[0:3]
	v_mfma_f32_16x16x32_bf16 v[52:55], v[170:173], v[186:189], v[52:55]
	v_mfma_f32_16x16x32_bf16 v[48:51], v[178:181], v[186:189], v[48:51]
	v_mfma_f32_16x16x32_bf16 v[36:39], v[170:173], v[194:197], v[36:39]
	v_mfma_f32_16x16x32_bf16 v[32:35], v[178:181], v[194:197], v[32:35]
	v_mfma_f32_16x16x32_bf16 v[20:23], v[170:173], v[202:205], v[20:23]
	v_mfma_f32_16x16x32_bf16 v[16:19], v[178:181], v[202:205], v[16:19]
	v_mfma_f32_16x16x32_bf16 v[4:7], v[170:173], v[230:233], v[4:7]
	v_mfma_f32_16x16x32_bf16 v[0:3], v[178:181], v[230:233], v[0:3]
	s_setprio 0
	s_barrier
	s_add_i32 s39, s38, 2
	s_add_u32 s54, s54, 0x100
	s_addc_u32 s55, s55, 0
	s_cmp_gt_u32 s38, 21
	s_cbranch_scc1 .LBB0_129
	s_mov_b32 s38, s39
	s_cmp_lt_i32 s38, 16
	s_cbranch_scc1 .LBB0_121
	s_branch .LBB0_120

; #define PG8_STAGE(bufoff, gbase, voff) do { _Pragma("unroll") for (int _i = 0; _i < 2; ++_i) \
;         __builtin_amdgcn_global_load_lds((const unsigned*)((const char*)(gbase) + (voff)[_i]), (PG8_LAS unsigned*)(lds + (bufoff) + ldsw + _i * 8192), 16, 0, 0); } while (0)
; #define PG8_LDA(dst, b, h) do { _Pragma("unroll") for (int m = 0; m < 4; ++m) _Pragma("unroll") for (int k = 0; k < 2; ++k) dst[m][k] = *(const PG8_LAS bf16x8*)(lds + PG8_SA(b, h) + aoff + m * 2048 + k * 1024); } while (0)
; #define PG8_LDB(dst, b, h) do { _Pragma("unroll") for (int n = 0; n < 2; ++n) _Pragma("unroll") for (int k = 0; k < 2; ++k) dst[n][k] = *(const PG8_LAS bf16x8*)(lds + PG8_SB(b, h) + boff + n * 2048 + k * 1024); } while (0)
; #define PG8_MMA(ai, bj, At, Bt) do { __builtin_amdgcn_s_setprio(1); _Pragma("unroll") for (int m = 0; m < 4; ++m) _Pragma("unroll") for (int n = 0; n < 2; ++n) _Pragma("unroll") for (int k = 0; k < 2; ++k) \
;         acc[ai][bj][m][n] = __builtin_amdgcn_mfma_f32_16x16x32_bf16(Bt[n][k], At[m][k], acc[ai][bj][m][n], 0, 0, 0); __builtin_amdgcn_s_setprio(0); } while (0)
; #define PG8_WAIT_V(n) asm volatile("s_waitcnt vmcnt(" #n ")" ::: "memory")
; #define PG8_WAIT_L(n) asm volatile("s_waitcnt lgkmcnt(" #n ")" ::: "memory")
; #define PG8_BAR __builtin_amdgcn_s_barrier()
; #define PG8_SCHED __builtin_amdgcn_sched_barrier(0)
; template <class Epi, class Sched, bool ALIGN_EPI = false, bool SP2 = false, class Hook = NoHook>
; __device__ __forceinline__ void gemm_phase(PG8_LAS unsigned char* lds, const Gemm g, const Sched& S, const Epi& E, int tid, const Hook& H = Hook()) {
;     ...
;             PG8_LDB(B0, 0, 0); PG8_LDB(B1, 0, 1); PG8_SCHED; PG8_LDA(At, 0, 0); PG8_STAGE(PG8_SA(1, 1), a1 + hstep, voffA);
;             PG8_WAIT_V(8); PG8_WAIT_L(0); PG8_BAR; PG8_MMA(0, 0, At, B0); PG8_MMA(0, 1, At, B1); PG8_BAR; PG8_SCHED;
;             PG8_LDA(At, 0, 1); PG8_STAGE(PG8_SB(0, 0), b2, voffB); PG8_STAGE(PG8_SB(0, 1), b2 + hstep, voffB); PG8_STAGE(PG8_SA(0, 0), a2, voffA);
.LBB0_154:
	s_add_u32 s0, s62, 0xfffc0080
	s_addc_u32 s1, s63, -1
	s_add_i32 s39, 0, 0x10000
	s_cmp_eq_u32 s38, 12
	s_cselect_b32 s65, s47, s1
	s_cselect_b32 s64, s94, s0
	s_cselect_b32 s49, s45, vcc_hi
	s_cselect_b32 s48, s95, vcc_lo
	s_add_i32 s75, 0, 0x14000
	v_add_u32_e32 v152, s39, v142
	v_add_u32_e32 v168, s75, v142
	ds_read_b128 v[138:141], v152
	ds_read_b128 v[144:147], v152 offset:1024
	ds_read_b128 v[148:151], v152 offset:2048
	ds_read_b128 v[152:155], v152 offset:3072
	ds_read_b128 v[156:159], v168
	ds_read_b128 v[160:163], v168 offset:1024
	ds_read_b128 v[164:167], v168 offset:2048
	ds_read_b128 v[168:171], v168 offset:3072
	v_lshl_add_u64 v[204:205], s[62:63], 0, v[132:133]
	s_add_i32 m0, s61, 0xc000
	ds_read_b128 v[172:175], v143
	ds_read_b128 v[176:179], v143 offset:1024
	ds_read_b128 v[180:183], v143 offset:2048
	ds_read_b128 v[184:187], v143 offset:3072
	ds_read_b128 v[188:191], v143 offset:4096
	ds_read_b128 v[192:195], v143 offset:5120
	ds_read_b128 v[196:199], v143 offset:6144
	ds_read_b128 v[200:203], v143 offset:7168
	global_load_lds_dwordx4 v[204:205], off
	v_lshl_add_u64 v[204:205], s[62:63], 0, v[134:135]
	s_add_i32 m0, s61, 0xe000
	s_nop 0
	global_load_lds_dwordx4 v[204:205], off
	s_waitcnt vmcnt(8)
	s_waitcnt lgkmcnt(0)
	s_barrier
	s_setprio 1
	v_mfma_f32_16x16x32_bf16 v[126:129], v[138:141], v[172:175], v[126:129]
	v_mfma_f32_16x16x32_bf16 v[122:125], v[148:151], v[172:175], v[122:125]
	v_mfma_f32_16x16x32_bf16 v[118:121], v[138:141], v[180:183], v[118:121]
	v_mfma_f32_16x16x32_bf16 v[106:109], v[148:151], v[180:183], v[106:109]
	v_mfma_f32_16x16x32_bf16 v[102:105], v[138:141], v[188:191], v[102:105]
	v_mfma_f32_16x16x32_bf16 v[92:95], v[148:151], v[188:191], v[92:95]
	v_mfma_f32_16x16x32_bf16 v[84:87], v[138:141], v[196:199], v[84:87]
	v_mfma_f32_16x16x32_bf16 v[76:79], v[148:151], v[196:199], v[76:79]
	v_mfma_f32_16x16x32_bf16 v[126:129], v[144:147], v[176:179], v[126:129]
	v_mfma_f32_16x16x32_bf16 v[122:125], v[152:155], v[176:179], v[122:125]
	v_mfma_f32_16x16x32_bf16 v[118:121], v[144:147], v[184:187], v[118:121]
	v_mfma_f32_16x16x32_bf16 v[106:109], v[152:155], v[184:187], v[106:109]
	v_mfma_f32_16x16x32_bf16 v[102:105], v[144:147], v[192:195], v[102:105]
	v_mfma_f32_16x16x32_bf16 v[92:95], v[152:155], v[192:195], v[92:95]
	v_mfma_f32_16x16x32_bf16 v[84:87], v[144:147], v[200:203], v[84:87]
	v_mfma_f32_16x16x32_bf16 v[76:79], v[152:155], v[200:203], v[76:79]
	v_mfma_f32_16x16x32_bf16 v[114:117], v[156:159], v[172:175], v[114:117]
	v_mfma_f32_16x16x32_bf16 v[110:113], v[164:167], v[172:175], v[110:113]
	v_mfma_f32_16x16x32_bf16 v[98:101], v[156:159], v[180:183], v[98:101]
	v_mfma_f32_16x16x32_bf16 v[88:91], v[164:167], v[180:183], v[88:91]
	v_mfma_f32_16x16x32_bf16 v[80:83], v[156:159], v[188:191], v[80:83]
	v_mfma_f32_16x16x32_bf16 v[72:75], v[164:167], v[188:191], v[72:75]
	v_mfma_f32_16x16x32_bf16 v[68:71], v[156:159], v[196:199], v[68:71]
	v_mfma_f32_16x16x32_bf16 v[64:67], v[164:167], v[196:199], v[64:67]
	v_mfma_f32_16x16x32_bf16 v[114:117], v[160:163], v[176:179], v[114:117]
	v_mfma_f32_16x16x32_bf16 v[110:113], v[168:171], v[176:179], v[110:113]
	v_mfma_f32_16x16x32_bf16 v[98:101], v[160:163], v[184:187], v[98:101]
	v_mfma_f32_16x16x32_bf16 v[88:91], v[168:171], v[184:187], v[88:91]
	v_mfma_f32_16x16x32_bf16 v[80:83], v[160:163], v[192:195], v[80:83]
	v_mfma_f32_16x16x32_bf16 v[72:75], v[168:171], v[192:195], v[72:75]
	v_mfma_f32_16x16x32_bf16 v[68:71], v[160:163], v[200:203], v[68:71]
	v_mfma_f32_16x16x32_bf16 v[64:67], v[168:171], v[200:203], v[64:67]
	s_setprio 0
	s_barrier
	s_add_i32 s0, s39, s27
	v_lshl_add_u64 v[204:205], s[48:49], 0, v[96:97]
	s_mov_b32 m0, s0
	ds_read_b128 v[172:175], v143 offset:16384
	ds_read_b128 v[176:179], v143 offset:17408
	ds_read_b128 v[180:183], v143 offset:18432
	ds_read_b128 v[184:187], v143 offset:19456
	ds_read_b128 v[188:191], v143 offset:20480
	ds_read_b128 v[192:195], v143 offset:21504
	ds_read_b128 v[196:199], v143 offset:22528
	ds_read_b128 v[200:203], v143 offset:23552
	global_load_lds_dwordx4 v[204:205], off
	s_add_i32 m0, s0, 0x2000
	s_add_u32 s0, s48, 0x40000
	v_lshl_add_u64 v[206:207], s[48:49], 0, v[130:131]
	s_addc_u32 s1, s49, 0
	s_add_i32 s39, s75, s27
	global_load_lds_dwordx4 v[206:207], off
	v_lshl_add_u64 v[208:209], s[0:1], 0, v[96:97]
	s_mov_b32 m0, s39
	v_lshl_add_u64 v[230:231], s[64:65], 0, v[130:131]
	global_load_lds_dwordx4 v[208:209], off
	v_lshl_add_u64 v[208:209], s[0:1], 0, v[130:131]
	s_add_i32 m0, s39, 0x2000
	s_nop 0
	global_load_lds_dwordx4 v[208:209], off
	v_lshl_add_u64 v[208:209], s[64:65], 0, v[96:97]
	s_mov_b32 m0, s61
	s_nop 0
	global_load_lds_dwordx4 v[208:209], off
	s_mov_b32 m0, s72
	s_nop 0
	global_load_lds_dwordx4 v[230:231], off
	s_waitcnt vmcnt(8)
	s_waitcnt lgkmcnt(0)
	s_barrier
; #define PG8_STAGE(bufoff, gbase, voff) do { _Pragma("unroll") for (int _i = 0; _i < 2; ++_i) \
;         __builtin_amdgcn_global_load_lds((const unsigned*)((const char*)(gbase) + (voff)[_i]), (PG8_LAS unsigned*)(lds + (bufoff) + ldsw + _i * 8192), 16, 0, 0); } while (0)
; #define PG8_LDA(dst, b, h) do { _Pragma("unroll") for (int m = 0; m < 4; ++m) _Pragma("unroll") for (int k = 0; k < 2; ++k) dst[m][k] = *(const PG8_LAS bf16x8*)(lds + PG8_SA(b, h) + aoff + m * 2048 + k * 1024); } while (0)
; #define PG8_LDB(dst, b, h) do { _Pragma("unroll") for (int n = 0; n < 2; ++n) _Pragma("unroll") for (int k = 0; k < 2; ++k) dst[n][k] = *(const PG8_LAS bf16x8*)(lds + PG8_SB(b, h) + boff + n * 2048 + k * 1024); } while (0)
; #define PG8_MMA(ai, bj, At, Bt) do { __builtin_amdgcn_s_setprio(1); _Pragma("unroll") for (int m = 0; m < 4; ++m) _Pragma("unroll") for (int n = 0; n < 2; ++n) _Pragma("unroll") for (int k = 0; k < 2; ++k) \
;         acc[ai][bj][m][n] = __builtin_amdgcn_mfma_f32_16x16x32_bf16(Bt[n][k], At[m][k], acc[ai][bj][m][n], 0, 0, 0); __builtin_amdgcn_s_setprio(0); } while (0)
; #define PG8_WAIT_V(n) asm volatile("s_waitcnt vmcnt(" #n ")" ::: "memory")
; #define PG8_WAIT_L(n) asm volatile("s_waitcnt lgkmcnt(" #n ")" ::: "memory")
; #define PG8_BAR __builtin_amdgcn_s_barrier()
; #define PG8_SCHED __builtin_amdgcn_sched_barrier(0)
; template <class Epi, class Sched, bool ALIGN_EPI = false, bool SP2 = false, class Hook = NoHook>
; __device__ __forceinline__ void gemm_phase(PG8_LAS unsigned char* lds, const Gemm g, const Sched& S, const Epi& E, int tid, const Hook& H = Hook()) {
;     ...
;             PG8_WAIT_V(8); PG8_WAIT_L(0); PG8_BAR; PG8_MMA(1, 0, At, B0); PG8_MMA(1, 1, At, B1); PG8_BAR; PG8_SCHED;
;             PG8_LDB(B0, 1, 0); PG8_LDB(B1, 1, 1); PG8_SCHED; PG8_LDA(At, 1, 0); PG8_STAGE(PG8_SA(0, 1), a2 + hstep, voffA);
;             PG8_WAIT_V(8); PG8_WAIT_L(0); PG8_BAR; PG8_MMA(0, 0, At, B0); PG8_MMA(0, 1, At, B1); PG8_BAR; PG8_SCHED;
	s_setprio 1
	v_mfma_f32_16x16x32_bf16 v[60:63], v[138:141], v[172:175], v[60:63]
	v_mfma_f32_16x16x32_bf16 v[56:59], v[148:151], v[172:175], v[56:59]
	v_mfma_f32_16x16x32_bf16 v[52:55], v[138:141], v[180:183], v[52:55]
	v_mfma_f32_16x16x32_bf16 v[40:43], v[148:151], v[180:183], v[40:43]
	v_mfma_f32_16x16x32_bf16 v[36:39], v[138:141], v[188:191], v[36:39]
	v_mfma_f32_16x16x32_bf16 v[24:27], v[148:151], v[188:191], v[24:27]
	v_mfma_f32_16x16x32_bf16 v[20:23], v[138:141], v[196:199], v[20:23]
	v_mfma_f32_16x16x32_bf16 v[8:11], v[148:151], v[196:199], v[8:11]
	v_mfma_f32_16x16x32_bf16 v[60:63], v[144:147], v[176:179], v[60:63]
	v_mfma_f32_16x16x32_bf16 v[56:59], v[152:155], v[176:179], v[56:59]
	v_mfma_f32_16x16x32_bf16 v[52:55], v[144:147], v[184:187], v[52:55]
	v_mfma_f32_16x16x32_bf16 v[40:43], v[152:155], v[184:187], v[40:43]
	v_mfma_f32_16x16x32_bf16 v[36:39], v[144:147], v[192:195], v[36:39]
	v_mfma_f32_16x16x32_bf16 v[24:27], v[152:155], v[192:195], v[24:27]
	v_mfma_f32_16x16x32_bf16 v[20:23], v[144:147], v[200:203], v[20:23]
	v_mfma_f32_16x16x32_bf16 v[8:11], v[152:155], v[200:203], v[8:11]
	v_mfma_f32_16x16x32_bf16 v[48:51], v[156:159], v[172:175], v[48:51]
	v_mfma_f32_16x16x32_bf16 v[44:47], v[164:167], v[172:175], v[44:47]
	v_mfma_f32_16x16x32_bf16 v[32:35], v[156:159], v[180:183], v[32:35]
	v_mfma_f32_16x16x32_bf16 v[28:31], v[164:167], v[180:183], v[28:31]
	v_mfma_f32_16x16x32_bf16 v[16:19], v[156:159], v[188:191], v[16:19]
	v_mfma_f32_16x16x32_bf16 v[12:15], v[164:167], v[188:191], v[12:15]
	v_mfma_f32_16x16x32_bf16 v[4:7], v[156:159], v[196:199], v[4:7]
	v_mfma_f32_16x16x32_bf16 v[0:3], v[164:167], v[196:199], v[0:3]
	v_mfma_f32_16x16x32_bf16 v[48:51], v[160:163], v[176:179], v[48:51]
	v_mfma_f32_16x16x32_bf16 v[44:47], v[168:171], v[176:179], v[44:47]
	v_mfma_f32_16x16x32_bf16 v[32:35], v[160:163], v[184:187], v[32:35]
	v_mfma_f32_16x16x32_bf16 v[28:31], v[168:171], v[184:187], v[28:31]
	v_mfma_f32_16x16x32_bf16 v[16:19], v[160:163], v[192:195], v[16:19]
	v_mfma_f32_16x16x32_bf16 v[12:15], v[168:171], v[192:195], v[12:15]
	v_mfma_f32_16x16x32_bf16 v[4:7], v[160:163], v[200:203], v[4:7]
	v_mfma_f32_16x16x32_bf16 v[0:3], v[168:171], v[200:203], v[0:3]
	s_setprio 0
	s_barrier
	s_add_i32 s39, 0, 0x18000
	s_add_i32 s75, 0, 0x1c000
	v_add_u32_e32 v152, s39, v142
	v_add_u32_e32 v168, s75, v142
	ds_read_b128 v[138:141], v152
	ds_read_b128 v[144:147], v152 offset:1024
	ds_read_b128 v[148:151], v152 offset:2048
	ds_read_b128 v[152:155], v152 offset:3072
	ds_read_b128 v[156:159], v168
	ds_read_b128 v[160:163], v168 offset:1024
	ds_read_b128 v[164:167], v168 offset:2048
	ds_read_b128 v[168:171], v168 offset:3072
	s_add_u32 s0, s64, 0x40000
	s_addc_u32 s1, s65, 0
	s_mov_b32 m0, s73
	v_lshl_add_u64 v[232:233], s[0:1], 0, v[96:97]
	ds_read_b128 v[172:175], v143 offset:32768
	ds_read_b128 v[176:179], v143 offset:33792
	ds_read_b128 v[180:183], v143 offset:34816
	ds_read_b128 v[184:187], v143 offset:35840
	ds_read_b128 v[188:191], v143 offset:36864
	ds_read_b128 v[192:195], v143 offset:37888
	ds_read_b128 v[196:199], v143 offset:38912
	ds_read_b128 v[200:203], v143 offset:39936
	global_load_lds_dwordx4 v[232:233], off
	v_lshl_add_u64 v[232:233], s[0:1], 0, v[130:131]
	s_mov_b32 m0, s74
	s_nop 0
	global_load_lds_dwordx4 v[232:233], off
	s_waitcnt vmcnt(8)
	s_waitcnt lgkmcnt(0)
	s_barrier
	s_setprio 1
	v_mfma_f32_16x16x32_bf16 v[126:129], v[138:141], v[172:175], v[126:129]
	v_mfma_f32_16x16x32_bf16 v[122:125], v[148:151], v[172:175], v[122:125]
	v_mfma_f32_16x16x32_bf16 v[118:121], v[138:141], v[180:183], v[118:121]
	v_mfma_f32_16x16x32_bf16 v[106:109], v[148:151], v[180:183], v[106:109]
	v_mfma_f32_16x16x32_bf16 v[102:105], v[138:141], v[188:191], v[102:105]
	v_mfma_f32_16x16x32_bf16 v[92:95], v[148:151], v[188:191], v[92:95]
	v_mfma_f32_16x16x32_bf16 v[84:87], v[138:141], v[196:199], v[84:87]
	v_mfma_f32_16x16x32_bf16 v[76:79], v[148:151], v[196:199], v[76:79]
	v_mfma_f32_16x16x32_bf16 v[126:129], v[144:147], v[176:179], v[126:129]
	v_mfma_f32_16x16x32_bf16 v[122:125], v[152:155], v[176:179], v[122:125]
	v_mfma_f32_16x16x32_bf16 v[118:121], v[144:147], v[184:187], v[118:121]
	v_mfma_f32_16x16x32_bf16 v[106:109], v[152:155], v[184:187], v[106:109]
	v_mfma_f32_16x16x32_bf16 v[102:105], v[144:147], v[192:195], v[102:105]
	v_mfma_f32_16x16x32_bf16 v[92:95], v[152:155], v[192:195], v[92:95]
	v_mfma_f32_16x16x32_bf16 v[84:87], v[144:147], v[200:203], v[84:87]
	v_mfma_f32_16x16x32_bf16 v[76:79], v[152:155], v[200:203], v[76:79]
	v_mfma_f32_16x16x32_bf16 v[114:117], v[156:159], v[172:175], v[114:117]
	v_mfma_f32_16x16x32_bf16 v[110:113], v[164:167], v[172:175], v[110:113]
	v_mfma_f32_16x16x32_bf16 v[98:101], v[156:159], v[180:183], v[98:101]
	v_mfma_f32_16x16x32_bf16 v[88:91], v[164:167], v[180:183], v[88:91]
	v_mfma_f32_16x16x32_bf16 v[80:83], v[156:159], v[188:191], v[80:83]
	v_mfma_f32_16x16x32_bf16 v[72:75], v[164:167], v[188:191], v[72:75]
	v_mfma_f32_16x16x32_bf16 v[68:71], v[156:159], v[196:199], v[68:71]
	v_mfma_f32_16x16x32_bf16 v[64:67], v[164:167], v[196:199], v[64:67]
	v_mfma_f32_16x16x32_bf16 v[114:117], v[160:163], v[176:179], v[114:117]
	v_mfma_f32_16x16x32_bf16 v[110:113], v[168:171], v[176:179], v[110:113]
	v_mfma_f32_16x16x32_bf16 v[98:101], v[160:163], v[184:187], v[98:101]
	v_mfma_f32_16x16x32_bf16 v[88:91], v[168:171], v[184:187], v[88:91]
	v_mfma_f32_16x16x32_bf16 v[80:83], v[160:163], v[192:195], v[80:83]
	v_mfma_f32_16x16x32_bf16 v[72:75], v[168:171], v[192:195], v[72:75]
	v_mfma_f32_16x16x32_bf16 v[68:71], v[160:163], v[200:203], v[68:71]
	v_mfma_f32_16x16x32_bf16 v[64:67], v[168:171], v[200:203], v[64:67]
	s_setprio 0
	s_barrier
; #define PG8_STAGE(bufoff, gbase, voff) do { _Pragma("unroll") for (int _i = 0; _i < 2; ++_i) \
;         __builtin_amdgcn_global_load_lds((const unsigned*)((const char*)(gbase) + (voff)[_i]), (PG8_LAS unsigned*)(lds + (bufoff) + ldsw + _i * 8192), 16, 0, 0); } while (0)
; #define PG8_LDA(dst, b, h) do { _Pragma("unroll") for (int m = 0; m < 4; ++m) _Pragma("unroll") for (int k = 0; k < 2; ++k) dst[m][k] = *(const PG8_LAS bf16x8*)(lds + PG8_SA(b, h) + aoff + m * 2048 + k * 1024); } while (0)
; #define PG8_MMA(ai, bj, At, Bt) do { __builtin_amdgcn_s_setprio(1); _Pragma("unroll") for (int m = 0; m < 4; ++m) _Pragma("unroll") for (int n = 0; n < 2; ++n) _Pragma("unroll") for (int k = 0; k < 2; ++k) \
;         acc[ai][bj][m][n] = __builtin_amdgcn_mfma_f32_16x16x32_bf16(Bt[n][k], At[m][k], acc[ai][bj][m][n], 0, 0, 0); __builtin_amdgcn_s_setprio(0); } while (0)
; #define PG8_WAIT_V(n) asm volatile("s_waitcnt vmcnt(" #n ")" ::: "memory")
; #define PG8_WAIT_L(n) asm volatile("s_waitcnt lgkmcnt(" #n ")" ::: "memory")
; #define PG8_BAR __builtin_amdgcn_s_barrier()
; #define PG8_SCHED __builtin_amdgcn_sched_barrier(0)
; template <class Epi, class Sched, bool ALIGN_EPI = false, bool SP2 = false, class Hook = NoHook>
; __device__ __forceinline__ void gemm_phase(PG8_LAS unsigned char* lds, const Gemm g, const Sched& S, const Epi& E, int tid, const Hook& H = Hook()) {
;     ...
;             PG8_LDA(At, 1, 1); PG8_STAGE(PG8_SB(1, 0), b3, voffB); PG8_STAGE(PG8_SB(1, 1), b3 + hstep, voffB); PG8_STAGE(PG8_SA(1, 0), a3, voffA);
;             PG8_WAIT_V(8); PG8_WAIT_L(0); PG8_BAR; PG8_MMA(1, 0, At, B0); PG8_MMA(1, 1, At, B1); PG8_BAR; PG8_SCHED;
	s_add_i32 s0, s39, s27
	v_lshl_add_u64 v[204:205], v[204:205], 0, s[4:5]
	s_mov_b32 m0, s0
	ds_read_b128 v[172:175], v143 offset:49152
	ds_read_b128 v[176:179], v143 offset:50176
	ds_read_b128 v[180:183], v143 offset:51200
	ds_read_b128 v[184:187], v143 offset:52224
	ds_read_b128 v[188:191], v143 offset:53248
	ds_read_b128 v[192:195], v143 offset:54272
	ds_read_b128 v[196:199], v143 offset:55296
	ds_read_b128 v[200:203], v143 offset:56320
	global_load_lds_dwordx4 v[204:205], off
	s_add_i32 m0, s0, 0x2000
	s_add_u32 s0, s48, 0x40080
	v_lshl_add_u64 v[204:205], v[206:207], 0, s[4:5]
	s_addc_u32 s1, s49, 0
	s_add_i32 s39, s75, s27
	global_load_lds_dwordx4 v[204:205], off
	v_lshl_add_u64 v[204:205], s[0:1], 0, v[96:97]
	s_mov_b32 m0, s39
	s_nop 0
	global_load_lds_dwordx4 v[204:205], off
	v_lshl_add_u64 v[204:205], s[0:1], 0, v[130:131]
	s_add_i32 m0, s39, 0x2000
	s_nop 0
	global_load_lds_dwordx4 v[204:205], off
	v_lshl_add_u64 v[204:205], v[208:209], 0, s[4:5]
	s_mov_b32 m0, s77
	s_nop 0
	global_load_lds_dwordx4 v[204:205], off
	v_lshl_add_u64 v[204:205], v[230:231], 0, s[4:5]
	s_mov_b32 m0, s82
	s_nop 0
	global_load_lds_dwordx4 v[204:205], off
	s_waitcnt vmcnt(8)
	s_waitcnt lgkmcnt(0)
	s_barrier
	s_setprio 1
	v_mfma_f32_16x16x32_bf16 v[60:63], v[138:141], v[172:175], v[60:63]
	v_mfma_f32_16x16x32_bf16 v[56:59], v[148:151], v[172:175], v[56:59]
	v_mfma_f32_16x16x32_bf16 v[52:55], v[138:141], v[180:183], v[52:55]
	v_mfma_f32_16x16x32_bf16 v[40:43], v[148:151], v[180:183], v[40:43]
	v_mfma_f32_16x16x32_bf16 v[36:39], v[138:141], v[188:191], v[36:39]
	v_mfma_f32_16x16x32_bf16 v[24:27], v[148:151], v[188:191], v[24:27]
	v_mfma_f32_16x16x32_bf16 v[20:23], v[138:141], v[196:199], v[20:23]
	v_mfma_f32_16x16x32_bf16 v[8:11], v[148:151], v[196:199], v[8:11]
	v_mfma_f32_16x16x32_bf16 v[60:63], v[144:147], v[176:179], v[60:63]
	v_mfma_f32_16x16x32_bf16 v[56:59], v[152:155], v[176:179], v[56:59]
	v_mfma_f32_16x16x32_bf16 v[52:55], v[144:147], v[184:187], v[52:55]
	v_mfma_f32_16x16x32_bf16 v[40:43], v[152:155], v[184:187], v[40:43]
	v_mfma_f32_16x16x32_bf16 v[36:39], v[144:147], v[192:195], v[36:39]
	v_mfma_f32_16x16x32_bf16 v[24:27], v[152:155], v[192:195], v[24:27]
	v_mfma_f32_16x16x32_bf16 v[20:23], v[144:147], v[200:203], v[20:23]
	v_mfma_f32_16x16x32_bf16 v[8:11], v[152:155], v[200:203], v[8:11]
	v_mfma_f32_16x16x32_bf16 v[48:51], v[156:159], v[172:175], v[48:51]
	v_mfma_f32_16x16x32_bf16 v[44:47], v[164:167], v[172:175], v[44:47]
	v_mfma_f32_16x16x32_bf16 v[32:35], v[156:159], v[180:183], v[32:35]
	v_mfma_f32_16x16x32_bf16 v[28:31], v[164:167], v[180:183], v[28:31]
	v_mfma_f32_16x16x32_bf16 v[16:19], v[156:159], v[188:191], v[16:19]
	v_mfma_f32_16x16x32_bf16 v[12:15], v[164:167], v[188:191], v[12:15]
	v_mfma_f32_16x16x32_bf16 v[4:7], v[156:159], v[196:199], v[4:7]
	v_mfma_f32_16x16x32_bf16 v[0:3], v[164:167], v[196:199], v[0:3]
	v_mfma_f32_16x16x32_bf16 v[48:51], v[160:163], v[176:179], v[48:51]
	v_mfma_f32_16x16x32_bf16 v[44:47], v[168:171], v[176:179], v[44:47]
	v_mfma_f32_16x16x32_bf16 v[32:35], v[160:163], v[184:187], v[32:35]
	v_mfma_f32_16x16x32_bf16 v[28:31], v[168:171], v[184:187], v[28:31]
	v_mfma_f32_16x16x32_bf16 v[16:19], v[160:163], v[192:195], v[16:19]
	v_mfma_f32_16x16x32_bf16 v[12:15], v[168:171], v[192:195], v[12:15]
	v_mfma_f32_16x16x32_bf16 v[4:7], v[160:163], v[200:203], v[4:7]
	v_mfma_f32_16x16x32_bf16 v[0:3], v[168:171], v[200:203], v[0:3]
	s_setprio 0
	s_barrier
	s_add_i32 s38, s38, 2
	s_add_u32 s62, s62, 0x100
	s_addc_u32 s63, s63, 0
	s_add_u32 vcc_lo, vcc_lo, 0x100
	s_addc_u32 vcc_hi, vcc_hi, 0
	s_cmp_gt_u32 s38, 13
	s_cbranch_scc0 .LBB0_154
	s_and_b64 vcc, exec, s[34:35]
	s_cbranch_vccz .LBB0_157
	s_barrier

; #define PG8_STAGE(bufoff, gbase, voff) do { _Pragma("unroll") for (int _i = 0; _i < 2; ++_i) \
;         __builtin_amdgcn_global_load_lds((const unsigned*)((const char*)(gbase) + (voff)[_i]), (PG8_LAS unsigned*)(lds + (bufoff) + ldsw + _i * 8192), 16, 0, 0); } while (0)
; #define PG8_LDA(dst, b, h) do { _Pragma("unroll") for (int m = 0; m < 4; ++m) _Pragma("unroll") for (int k = 0; k < 2; ++k) dst[m][k] = *(const PG8_LAS bf16x8*)(lds + PG8_SA(b, h) + aoff + m * 2048 + k * 1024); } while (0)
; #define PG8_LDB(dst, b, h) do { _Pragma("unroll") for (int n = 0; n < 2; ++n) _Pragma("unroll") for (int k = 0; k < 2; ++k) dst[n][k] = *(const PG8_LAS bf16x8*)(lds + PG8_SB(b, h) + boff + n * 2048 + k * 1024); } while (0)
; #define PG8_MMA(ai, bj, At, Bt) do { __builtin_amdgcn_s_setprio(1); _Pragma("unroll") for (int m = 0; m < 4; ++m) _Pragma("unroll") for (int n = 0; n < 2; ++n) _Pragma("unroll") for (int k = 0; k < 2; ++k) \
;         acc[ai][bj][m][n] = __builtin_amdgcn_mfma_f32_16x16x32_bf16(Bt[n][k], At[m][k], acc[ai][bj][m][n], 0, 0, 0); __builtin_amdgcn_s_setprio(0); } while (0)
; #define PG8_WAIT_V(n) asm volatile("s_waitcnt vmcnt(" #n ")" ::: "memory")
; #define PG8_WAIT_L(n) asm volatile("s_waitcnt lgkmcnt(" #n ")" ::: "memory")
; #define PG8_BAR __builtin_amdgcn_s_barrier()
; #define PG8_SCHED __builtin_amdgcn_sched_barrier(0)
; template <class Epi, class Sched, bool ALIGN_EPI = false, bool SP2 = false, class Hook = NoHook>
; __device__ __forceinline__ void gemm_phase(PG8_LAS unsigned char* lds, const Gemm g, const Sched& S, const Epi& E, int tid, const Hook& H = Hook()) {
;     ...
;             PG8_LDB(B0, 0, 0); PG8_LDB(B1, 0, 1); PG8_SCHED; PG8_LDA(At, 0, 0); PG8_STAGE(PG8_SA(1, 1), a1 + hstep, voffA);
;             PG8_WAIT_V(8); PG8_WAIT_L(0); PG8_BAR; PG8_MMA(0, 0, At, B0); PG8_MMA(0, 1, At, B1); PG8_BAR; PG8_SCHED;
;             PG8_LDA(At, 0, 1); PG8_STAGE(PG8_SB(0, 0), b2, voffB); PG8_STAGE(PG8_SB(0, 1), b2 + hstep, voffB); PG8_STAGE(PG8_SA(0, 0), a2, voffA);
.LBB0_343:
	s_add_u32 s42, s0, 0xfffc0080
	s_addc_u32 s43, s1, -1
	s_add_i32 s76, 0, 0x10000
	s_cmp_eq_u32 s75, 12
	s_cselect_b32 s47, s35, s43
	s_cselect_b32 s46, s45, s42
	v_add_u32_e32 v96, s76, v231
	s_cselect_b32 s43, s55, s74
	s_cselect_b32 s42, s72, s73
	s_add_i32 s83, 0, 0x14000
	ds_read_b128 v[130:133], v96
	ds_read_b128 v[134:137], v96 offset:1024
	ds_read_b128 v[138:141], v96 offset:2048
	ds_read_b128 v[150:153], v96 offset:3072
	v_add_u32_e32 v96, s83, v231
	ds_read_b128 v[154:157], v96
	ds_read_b128 v[158:161], v96 offset:1024
	ds_read_b128 v[162:165], v96 offset:2048
	ds_read_b128 v[166:169], v96 offset:3072
	v_lshl_add_u64 v[202:203], s[0:1], 0, v[146:147]
	s_add_i32 m0, s26, 0xc000
	ds_read_b128 v[170:173], v232
	ds_read_b128 v[174:177], v232 offset:1024
	ds_read_b128 v[178:181], v232 offset:2048
	ds_read_b128 v[182:185], v232 offset:3072
	ds_read_b128 v[186:189], v232 offset:4096
	ds_read_b128 v[190:193], v232 offset:5120
	ds_read_b128 v[194:197], v232 offset:6144
	ds_read_b128 v[198:201], v232 offset:7168
	global_load_lds_dwordx4 v[202:203], off
	v_lshl_add_u64 v[202:203], s[0:1], 0, v[148:149]
	s_add_i32 m0, s26, 0xe000
	s_nop 0
	global_load_lds_dwordx4 v[202:203], off
	s_waitcnt vmcnt(8)
	s_waitcnt lgkmcnt(0)
	s_barrier
	s_setprio 1
	v_mfma_f32_16x16x32_bf16 v[126:129], v[130:133], v[170:173], v[126:129]
	v_mfma_f32_16x16x32_bf16 v[122:125], v[138:141], v[170:173], v[122:125]
	v_mfma_f32_16x16x32_bf16 v[110:113], v[130:133], v[178:181], v[110:113]
	v_mfma_f32_16x16x32_bf16 v[106:109], v[138:141], v[178:181], v[106:109]
	v_mfma_f32_16x16x32_bf16 v[92:95], v[130:133], v[186:189], v[92:95]
	v_mfma_f32_16x16x32_bf16 v[88:91], v[138:141], v[186:189], v[88:91]
	v_mfma_f32_16x16x32_bf16 v[76:79], v[130:133], v[194:197], v[76:79]
	v_mfma_f32_16x16x32_bf16 v[72:75], v[138:141], v[194:197], v[72:75]
	v_mfma_f32_16x16x32_bf16 v[126:129], v[134:137], v[174:177], v[126:129]
	v_mfma_f32_16x16x32_bf16 v[122:125], v[150:153], v[174:177], v[122:125]
	v_mfma_f32_16x16x32_bf16 v[110:113], v[134:137], v[182:185], v[110:113]
	v_mfma_f32_16x16x32_bf16 v[106:109], v[150:153], v[182:185], v[106:109]
	v_mfma_f32_16x16x32_bf16 v[92:95], v[134:137], v[190:193], v[92:95]
	v_mfma_f32_16x16x32_bf16 v[88:91], v[150:153], v[190:193], v[88:91]
	v_mfma_f32_16x16x32_bf16 v[76:79], v[134:137], v[198:201], v[76:79]
	v_mfma_f32_16x16x32_bf16 v[72:75], v[150:153], v[198:201], v[72:75]
	v_mfma_f32_16x16x32_bf16 v[118:121], v[154:157], v[170:173], v[118:121]
	v_mfma_f32_16x16x32_bf16 v[114:117], v[162:165], v[170:173], v[114:117]
	v_mfma_f32_16x16x32_bf16 v[102:105], v[154:157], v[178:181], v[102:105]
	v_mfma_f32_16x16x32_bf16 v[98:101], v[162:165], v[178:181], v[98:101]
	v_mfma_f32_16x16x32_bf16 v[84:87], v[154:157], v[186:189], v[84:87]
	v_mfma_f32_16x16x32_bf16 v[80:83], v[162:165], v[186:189], v[80:83]
	v_mfma_f32_16x16x32_bf16 v[68:71], v[154:157], v[194:197], v[68:71]
	v_mfma_f32_16x16x32_bf16 v[64:67], v[162:165], v[194:197], v[64:67]
	v_mfma_f32_16x16x32_bf16 v[118:121], v[158:161], v[174:177], v[118:121]
	v_mfma_f32_16x16x32_bf16 v[114:117], v[166:169], v[174:177], v[114:117]
	v_mfma_f32_16x16x32_bf16 v[102:105], v[158:161], v[182:185], v[102:105]
	v_mfma_f32_16x16x32_bf16 v[98:101], v[166:169], v[182:185], v[98:101]
	v_mfma_f32_16x16x32_bf16 v[84:87], v[158:161], v[190:193], v[84:87]
	v_mfma_f32_16x16x32_bf16 v[80:83], v[166:169], v[190:193], v[80:83]
	v_mfma_f32_16x16x32_bf16 v[68:71], v[158:161], v[198:201], v[68:71]
	v_mfma_f32_16x16x32_bf16 v[64:67], v[166:169], v[198:201], v[64:67]
	s_setprio 0
	s_barrier
	s_add_i32 s76, s76, s24
	v_lshl_add_u64 v[202:203], s[42:43], 0, v[142:143]
	s_mov_b32 m0, s76
	ds_read_b128 v[170:173], v232 offset:16384
	ds_read_b128 v[174:177], v232 offset:17408
	ds_read_b128 v[178:181], v232 offset:18432
	ds_read_b128 v[182:185], v232 offset:19456
	ds_read_b128 v[186:189], v232 offset:20480
	ds_read_b128 v[190:193], v232 offset:21504
	ds_read_b128 v[194:197], v232 offset:22528
	ds_read_b128 v[198:201], v232 offset:23552
	global_load_lds_dwordx4 v[202:203], off
	s_add_i32 m0, s76, 0x2000
	s_add_u32 s76, s42, 0x40000
	v_lshl_add_u64 v[204:205], s[42:43], 0, v[144:145]
	s_addc_u32 s77, s43, 0
	s_add_i32 s83, s83, s24
	global_load_lds_dwordx4 v[204:205], off
	v_lshl_add_u64 v[206:207], s[76:77], 0, v[142:143]
	s_mov_b32 m0, s83
	v_lshl_add_u64 v[208:209], s[46:47], 0, v[144:145]
	global_load_lds_dwordx4 v[206:207], off
	v_lshl_add_u64 v[206:207], s[76:77], 0, v[144:145]
	s_add_i32 m0, s83, 0x2000
	s_nop 0
	global_load_lds_dwordx4 v[206:207], off
	v_lshl_add_u64 v[206:207], s[46:47], 0, v[142:143]
	s_mov_b32 m0, s26
	s_nop 0
	global_load_lds_dwordx4 v[206:207], off
	s_mov_b32 m0, s27
	s_nop 0
	global_load_lds_dwordx4 v[208:209], off
	s_waitcnt vmcnt(8)
	s_waitcnt lgkmcnt(0)
	s_barrier
; #define PG8_STAGE(bufoff, gbase, voff) do { _Pragma("unroll") for (int _i = 0; _i < 2; ++_i) \
;         __builtin_amdgcn_global_load_lds((const unsigned*)((const char*)(gbase) + (voff)[_i]), (PG8_LAS unsigned*)(lds + (bufoff) + ldsw + _i * 8192), 16, 0, 0); } while (0)
; #define PG8_LDA(dst, b, h) do { _Pragma("unroll") for (int m = 0; m < 4; ++m) _Pragma("unroll") for (int k = 0; k < 2; ++k) dst[m][k] = *(const PG8_LAS bf16x8*)(lds + PG8_SA(b, h) + aoff + m * 2048 + k * 1024); } while (0)
; #define PG8_LDB(dst, b, h) do { _Pragma("unroll") for (int n = 0; n < 2; ++n) _Pragma("unroll") for (int k = 0; k < 2; ++k) dst[n][k] = *(const PG8_LAS bf16x8*)(lds + PG8_SB(b, h) + boff + n * 2048 + k * 1024); } while (0)
; #define PG8_MMA(ai, bj, At, Bt) do { __builtin_amdgcn_s_setprio(1); _Pragma("unroll") for (int m = 0; m < 4; ++m) _Pragma("unroll") for (int n = 0; n < 2; ++n) _Pragma("unroll") for (int k = 0; k < 2; ++k) \
;         acc[ai][bj][m][n] = __builtin_amdgcn_mfma_f32_16x16x32_bf16(Bt[n][k], At[m][k], acc[ai][bj][m][n], 0, 0, 0); __builtin_amdgcn_s_setprio(0); } while (0)
; #define PG8_WAIT_V(n) asm volatile("s_waitcnt vmcnt(" #n ")" ::: "memory")
; #define PG8_WAIT_L(n) asm volatile("s_waitcnt lgkmcnt(" #n ")" ::: "memory")
; #define PG8_BAR __builtin_amdgcn_s_barrier()
; #define PG8_SCHED __builtin_amdgcn_sched_barrier(0)
; template <class Epi, class Sched, bool ALIGN_EPI = false, bool SP2 = false, class Hook = NoHook>
; __device__ __forceinline__ void gemm_phase(PG8_LAS unsigned char* lds, const Gemm g, const Sched& S, const Epi& E, int tid, const Hook& H = Hook()) {
;     ...
;             PG8_WAIT_V(8); PG8_WAIT_L(0); PG8_BAR; PG8_MMA(1, 0, At, B0); PG8_MMA(1, 1, At, B1); PG8_BAR; PG8_SCHED;
;             PG8_LDB(B0, 1, 0); PG8_LDB(B1, 1, 1); PG8_SCHED; PG8_LDA(At, 1, 0); PG8_STAGE(PG8_SA(0, 1), a2 + hstep, voffA);
;             PG8_WAIT_V(8); PG8_WAIT_L(0); PG8_BAR; PG8_MMA(0, 0, At, B0); PG8_MMA(0, 1, At, B1); PG8_BAR; PG8_SCHED;
	s_setprio 1
	v_mfma_f32_16x16x32_bf16 v[60:63], v[130:133], v[170:173], v[60:63]
	v_mfma_f32_16x16x32_bf16 v[56:59], v[138:141], v[170:173], v[56:59]
	v_mfma_f32_16x16x32_bf16 v[44:47], v[130:133], v[178:181], v[44:47]
	v_mfma_f32_16x16x32_bf16 v[40:43], v[138:141], v[178:181], v[40:43]
	v_mfma_f32_16x16x32_bf16 v[28:31], v[130:133], v[186:189], v[28:31]
	v_mfma_f32_16x16x32_bf16 v[24:27], v[138:141], v[186:189], v[24:27]
	v_mfma_f32_16x16x32_bf16 v[12:15], v[130:133], v[194:197], v[12:15]
	v_mfma_f32_16x16x32_bf16 v[8:11], v[138:141], v[194:197], v[8:11]
	v_mfma_f32_16x16x32_bf16 v[60:63], v[134:137], v[174:177], v[60:63]
	v_mfma_f32_16x16x32_bf16 v[56:59], v[150:153], v[174:177], v[56:59]
	v_mfma_f32_16x16x32_bf16 v[44:47], v[134:137], v[182:185], v[44:47]
	v_mfma_f32_16x16x32_bf16 v[40:43], v[150:153], v[182:185], v[40:43]
	v_mfma_f32_16x16x32_bf16 v[28:31], v[134:137], v[190:193], v[28:31]
	v_mfma_f32_16x16x32_bf16 v[24:27], v[150:153], v[190:193], v[24:27]
	v_mfma_f32_16x16x32_bf16 v[12:15], v[134:137], v[198:201], v[12:15]
	v_mfma_f32_16x16x32_bf16 v[8:11], v[150:153], v[198:201], v[8:11]
	v_mfma_f32_16x16x32_bf16 v[52:55], v[154:157], v[170:173], v[52:55]
	v_mfma_f32_16x16x32_bf16 v[48:51], v[162:165], v[170:173], v[48:51]
	v_mfma_f32_16x16x32_bf16 v[36:39], v[154:157], v[178:181], v[36:39]
	v_mfma_f32_16x16x32_bf16 v[32:35], v[162:165], v[178:181], v[32:35]
	v_mfma_f32_16x16x32_bf16 v[20:23], v[154:157], v[186:189], v[20:23]
	v_mfma_f32_16x16x32_bf16 v[16:19], v[162:165], v[186:189], v[16:19]
	v_mfma_f32_16x16x32_bf16 v[4:7], v[154:157], v[194:197], v[4:7]
	v_mfma_f32_16x16x32_bf16 v[0:3], v[162:165], v[194:197], v[0:3]
	v_mfma_f32_16x16x32_bf16 v[52:55], v[158:161], v[174:177], v[52:55]
	v_mfma_f32_16x16x32_bf16 v[48:51], v[166:169], v[174:177], v[48:51]
	v_mfma_f32_16x16x32_bf16 v[36:39], v[158:161], v[182:185], v[36:39]
	v_mfma_f32_16x16x32_bf16 v[32:35], v[166:169], v[182:185], v[32:35]
	v_mfma_f32_16x16x32_bf16 v[20:23], v[158:161], v[190:193], v[20:23]
	v_mfma_f32_16x16x32_bf16 v[16:19], v[166:169], v[190:193], v[16:19]
	v_mfma_f32_16x16x32_bf16 v[4:7], v[158:161], v[198:201], v[4:7]
	v_mfma_f32_16x16x32_bf16 v[0:3], v[166:169], v[198:201], v[0:3]
	s_setprio 0
	s_barrier
	s_add_i32 s76, 0, 0x18000
	v_add_u32_e32 v96, s76, v231
	s_add_i32 s77, 0, 0x1c000
	ds_read_b128 v[130:133], v96
	ds_read_b128 v[134:137], v96 offset:1024
	ds_read_b128 v[138:141], v96 offset:2048
	ds_read_b128 v[150:153], v96 offset:3072
	v_add_u32_e32 v96, s77, v231
	ds_read_b128 v[154:157], v96
	ds_read_b128 v[158:161], v96 offset:1024
	ds_read_b128 v[162:165], v96 offset:2048
	ds_read_b128 v[166:169], v96 offset:3072
	s_add_u32 s46, s46, 0x40000
	s_addc_u32 s47, s47, 0
	s_mov_b32 m0, s58
	v_lshl_add_u64 v[234:235], s[46:47], 0, v[142:143]
	ds_read_b128 v[170:173], v232 offset:32768
	ds_read_b128 v[174:177], v232 offset:33792
	ds_read_b128 v[178:181], v232 offset:34816
	ds_read_b128 v[182:185], v232 offset:35840
	ds_read_b128 v[186:189], v232 offset:36864
	ds_read_b128 v[190:193], v232 offset:37888
	ds_read_b128 v[194:197], v232 offset:38912
	ds_read_b128 v[198:201], v232 offset:39936
	global_load_lds_dwordx4 v[234:235], off
	v_lshl_add_u64 v[234:235], s[46:47], 0, v[144:145]
	s_mov_b32 m0, s59
	s_nop 0
	global_load_lds_dwordx4 v[234:235], off
	s_waitcnt vmcnt(8)
	s_waitcnt lgkmcnt(0)
	s_barrier
	s_setprio 1
	v_mfma_f32_16x16x32_bf16 v[126:129], v[130:133], v[170:173], v[126:129]
	v_mfma_f32_16x16x32_bf16 v[122:125], v[138:141], v[170:173], v[122:125]
	v_mfma_f32_16x16x32_bf16 v[110:113], v[130:133], v[178:181], v[110:113]
	v_mfma_f32_16x16x32_bf16 v[106:109], v[138:141], v[178:181], v[106:109]
	v_mfma_f32_16x16x32_bf16 v[92:95], v[130:133], v[186:189], v[92:95]
	v_mfma_f32_16x16x32_bf16 v[88:91], v[138:141], v[186:189], v[88:91]
	v_mfma_f32_16x16x32_bf16 v[76:79], v[130:133], v[194:197], v[76:79]
	v_mfma_f32_16x16x32_bf16 v[72:75], v[138:141], v[194:197], v[72:75]
	v_mfma_f32_16x16x32_bf16 v[126:129], v[134:137], v[174:177], v[126:129]
	v_mfma_f32_16x16x32_bf16 v[122:125], v[150:153], v[174:177], v[122:125]
	v_mfma_f32_16x16x32_bf16 v[110:113], v[134:137], v[182:185], v[110:113]
	v_mfma_f32_16x16x32_bf16 v[106:109], v[150:153], v[182:185], v[106:109]
	v_mfma_f32_16x16x32_bf16 v[92:95], v[134:137], v[190:193], v[92:95]
	v_mfma_f32_16x16x32_bf16 v[88:91], v[150:153], v[190:193], v[88:91]
	v_mfma_f32_16x16x32_bf16 v[76:79], v[134:137], v[198:201], v[76:79]
	v_mfma_f32_16x16x32_bf16 v[72:75], v[150:153], v[198:201], v[72:75]
	v_mfma_f32_16x16x32_bf16 v[118:121], v[154:157], v[170:173], v[118:121]
	v_mfma_f32_16x16x32_bf16 v[114:117], v[162:165], v[170:173], v[114:117]
	v_mfma_f32_16x16x32_bf16 v[102:105], v[154:157], v[178:181], v[102:105]
	v_mfma_f32_16x16x32_bf16 v[98:101], v[162:165], v[178:181], v[98:101]
	v_mfma_f32_16x16x32_bf16 v[84:87], v[154:157], v[186:189], v[84:87]
	v_mfma_f32_16x16x32_bf16 v[80:83], v[162:165], v[186:189], v[80:83]
	v_mfma_f32_16x16x32_bf16 v[68:71], v[154:157], v[194:197], v[68:71]
	v_mfma_f32_16x16x32_bf16 v[64:67], v[162:165], v[194:197], v[64:67]
	v_mfma_f32_16x16x32_bf16 v[118:121], v[158:161], v[174:177], v[118:121]
	v_mfma_f32_16x16x32_bf16 v[114:117], v[166:169], v[174:177], v[114:117]
	v_mfma_f32_16x16x32_bf16 v[102:105], v[158:161], v[182:185], v[102:105]
	v_mfma_f32_16x16x32_bf16 v[98:101], v[166:169], v[182:185], v[98:101]
	v_mfma_f32_16x16x32_bf16 v[84:87], v[158:161], v[190:193], v[84:87]
	v_mfma_f32_16x16x32_bf16 v[80:83], v[166:169], v[190:193], v[80:83]
	v_mfma_f32_16x16x32_bf16 v[68:71], v[158:161], v[198:201], v[68:71]
	v_mfma_f32_16x16x32_bf16 v[64:67], v[166:169], v[198:201], v[64:67]
	s_setprio 0
	s_barrier
; #define PG8_STAGE(bufoff, gbase, voff) do { _Pragma("unroll") for (int _i = 0; _i < 2; ++_i) \
;         __builtin_amdgcn_global_load_lds((const unsigned*)((const char*)(gbase) + (voff)[_i]), (PG8_LAS unsigned*)(lds + (bufoff) + ldsw + _i * 8192), 16, 0, 0); } while (0)
; #define PG8_LDA(dst, b, h) do { _Pragma("unroll") for (int m = 0; m < 4; ++m) _Pragma("unroll") for (int k = 0; k < 2; ++k) dst[m][k] = *(const PG8_LAS bf16x8*)(lds + PG8_SA(b, h) + aoff + m * 2048 + k * 1024); } while (0)
; #define PG8_MMA(ai, bj, At, Bt) do { __builtin_amdgcn_s_setprio(1); _Pragma("unroll") for (int m = 0; m < 4; ++m) _Pragma("unroll") for (int n = 0; n < 2; ++n) _Pragma("unroll") for (int k = 0; k < 2; ++k) \
;         acc[ai][bj][m][n] = __builtin_amdgcn_mfma_f32_16x16x32_bf16(Bt[n][k], At[m][k], acc[ai][bj][m][n], 0, 0, 0); __builtin_amdgcn_s_setprio(0); } while (0)
; #define PG8_WAIT_V(n) asm volatile("s_waitcnt vmcnt(" #n ")" ::: "memory")
; #define PG8_WAIT_L(n) asm volatile("s_waitcnt lgkmcnt(" #n ")" ::: "memory")
; #define PG8_BAR __builtin_amdgcn_s_barrier()
; #define PG8_SCHED __builtin_amdgcn_sched_barrier(0)
; template <class Epi, class Sched, bool ALIGN_EPI = false, bool SP2 = false, class Hook = NoHook>
; __device__ __forceinline__ void gemm_phase(PG8_LAS unsigned char* lds, const Gemm g, const Sched& S, const Epi& E, int tid, const Hook& H = Hook()) {
;     ...
;             PG8_LDA(At, 1, 1); PG8_STAGE(PG8_SB(1, 0), b3, voffB); PG8_STAGE(PG8_SB(1, 1), b3 + hstep, voffB); PG8_STAGE(PG8_SA(1, 0), a3, voffA);
;             PG8_WAIT_V(8); PG8_WAIT_L(0); PG8_BAR; PG8_MMA(1, 0, At, B0); PG8_MMA(1, 1, At, B1); PG8_BAR; PG8_SCHED;
	s_add_i32 s46, s76, s24
	v_lshl_add_u64 v[202:203], v[202:203], 0, s[4:5]
	s_mov_b32 m0, s46
	ds_read_b128 v[170:173], v232 offset:49152
	ds_read_b128 v[174:177], v232 offset:50176
	ds_read_b128 v[178:181], v232 offset:51200
	ds_read_b128 v[182:185], v232 offset:52224
	ds_read_b128 v[186:189], v232 offset:53248
	ds_read_b128 v[190:193], v232 offset:54272
	ds_read_b128 v[194:197], v232 offset:55296
	ds_read_b128 v[198:201], v232 offset:56320
	global_load_lds_dwordx4 v[202:203], off
	s_add_i32 m0, s46, 0x2000
	s_add_u32 s42, s42, 0x40080
	v_lshl_add_u64 v[202:203], v[204:205], 0, s[4:5]
	s_addc_u32 s43, s43, 0
	s_add_i32 s46, s77, s24
	global_load_lds_dwordx4 v[202:203], off
	v_lshl_add_u64 v[202:203], s[42:43], 0, v[142:143]
	s_mov_b32 m0, s46
	s_nop 0
	global_load_lds_dwordx4 v[202:203], off
	v_lshl_add_u64 v[202:203], s[42:43], 0, v[144:145]
	s_add_i32 m0, s46, 0x2000
	s_nop 0
	global_load_lds_dwordx4 v[202:203], off
	v_lshl_add_u64 v[202:203], v[206:207], 0, s[4:5]
	s_mov_b32 m0, s65
	s_nop 0
	global_load_lds_dwordx4 v[202:203], off
	v_lshl_add_u64 v[202:203], v[208:209], 0, s[4:5]
	s_mov_b32 m0, s93
	s_nop 0
	global_load_lds_dwordx4 v[202:203], off
	s_waitcnt vmcnt(8)
	s_waitcnt lgkmcnt(0)
	s_barrier
	s_setprio 1
	v_mfma_f32_16x16x32_bf16 v[60:63], v[130:133], v[170:173], v[60:63]
	v_mfma_f32_16x16x32_bf16 v[56:59], v[138:141], v[170:173], v[56:59]
	v_mfma_f32_16x16x32_bf16 v[44:47], v[130:133], v[178:181], v[44:47]
	v_mfma_f32_16x16x32_bf16 v[40:43], v[138:141], v[178:181], v[40:43]
	v_mfma_f32_16x16x32_bf16 v[28:31], v[130:133], v[186:189], v[28:31]
	v_mfma_f32_16x16x32_bf16 v[24:27], v[138:141], v[186:189], v[24:27]
	v_mfma_f32_16x16x32_bf16 v[12:15], v[130:133], v[194:197], v[12:15]
	v_mfma_f32_16x16x32_bf16 v[8:11], v[138:141], v[194:197], v[8:11]
	v_mfma_f32_16x16x32_bf16 v[60:63], v[134:137], v[174:177], v[60:63]
	v_mfma_f32_16x16x32_bf16 v[56:59], v[150:153], v[174:177], v[56:59]
	v_mfma_f32_16x16x32_bf16 v[44:47], v[134:137], v[182:185], v[44:47]
	v_mfma_f32_16x16x32_bf16 v[40:43], v[150:153], v[182:185], v[40:43]
	v_mfma_f32_16x16x32_bf16 v[28:31], v[134:137], v[190:193], v[28:31]
	v_mfma_f32_16x16x32_bf16 v[24:27], v[150:153], v[190:193], v[24:27]
	v_mfma_f32_16x16x32_bf16 v[12:15], v[134:137], v[198:201], v[12:15]
	v_mfma_f32_16x16x32_bf16 v[8:11], v[150:153], v[198:201], v[8:11]
	v_mfma_f32_16x16x32_bf16 v[52:55], v[154:157], v[170:173], v[52:55]
	v_mfma_f32_16x16x32_bf16 v[48:51], v[162:165], v[170:173], v[48:51]
	v_mfma_f32_16x16x32_bf16 v[36:39], v[154:157], v[178:181], v[36:39]
	v_mfma_f32_16x16x32_bf16 v[32:35], v[162:165], v[178:181], v[32:35]
	v_mfma_f32_16x16x32_bf16 v[20:23], v[154:157], v[186:189], v[20:23]
	v_mfma_f32_16x16x32_bf16 v[16:19], v[162:165], v[186:189], v[16:19]
	v_mfma_f32_16x16x32_bf16 v[4:7], v[154:157], v[194:197], v[4:7]
	v_mfma_f32_16x16x32_bf16 v[0:3], v[162:165], v[194:197], v[0:3]
	v_mfma_f32_16x16x32_bf16 v[52:55], v[158:161], v[174:177], v[52:55]
	v_mfma_f32_16x16x32_bf16 v[48:51], v[166:169], v[174:177], v[48:51]
	v_mfma_f32_16x16x32_bf16 v[36:39], v[158:161], v[182:185], v[36:39]
	v_mfma_f32_16x16x32_bf16 v[32:35], v[166:169], v[182:185], v[32:35]
	v_mfma_f32_16x16x32_bf16 v[20:23], v[158:161], v[190:193], v[20:23]
	v_mfma_f32_16x16x32_bf16 v[16:19], v[166:169], v[190:193], v[16:19]
	v_mfma_f32_16x16x32_bf16 v[4:7], v[158:161], v[198:201], v[4:7]
	v_mfma_f32_16x16x32_bf16 v[0:3], v[166:169], v[198:201], v[0:3]
	s_setprio 0
	s_barrier
	s_add_i32 s75, s75, 2
	s_add_u32 s0, s0, 0x100
	s_addc_u32 s1, s1, 0
	s_add_u32 s73, s73, 0x100
	s_addc_u32 s74, s74, 0
	s_cmp_gt_u32 s75, 13
	s_cbranch_scc0 .LBB0_343
	s_and_b64 vcc, exec, s[18:19]
	s_cbranch_vccz .LBB0_346
	s_barrier
